# attention loop: cross-half row-max reduction moved into the rare rescale block; threshold decision taken on per-half maxima (on top of v040)
# speedup vs baseline: 1.0089x; 1.0015x over previous
; #define SBAR() __builtin_amdgcn_sched_barrier(0)
; template <int OFF> DEVFI s16x4 tr_read(int vb) { s16x4 r; asm volatile("ds_read_b64_tr_b16 %0, %1 offset:%2" : "=&v"(r) : "v"(vb), "i"(OFF) : "memory"); return r; }
; DEVFI void partialSM2(f32x16& p0, f32x16& p1, float& mhat, f32x16& negm, float& alpha, const float thr2, const bool first) {
;     float pmax = p0[0];
; #pragma unroll
;     for (int r = 1; r < 16; ++r) pmax = fmaxf(pmax, p0[r]);
; #pragma unroll
;     for (int r = 0; r < 16; ++r) pmax = fmaxf(pmax, p1[r]);
;     { auto rr = __builtin_amdgcn_permlane32_swap(__float_as_uint(pmax), __float_as_uint(pmax), false, false);
;       pmax = fmaxf(__uint_as_float(rr[0]), __uint_as_float(rr[1])); }
;     alpha = 1.f;
;     if (first || !__all(pmax <= thr2)) {
;         const float dl = first ? pmax : fmaxf(pmax, 0.f);
;         mhat += dl; alpha = first ? 1.f : __builtin_amdgcn_exp2f(-dl);
; #pragma unroll
;         for (int r = 0; r < 16; ++r) { p0[r] -= dl; p1[r] -= dl; }
; #pragma unroll
;         for (int r = 0; r < 16; ++r) negm[r] = -mhat;
;         asm volatile("" : "+v"(negm));
; template <int NCB, int D0> DEVFI void pv_one(f32x16& od, int vb, bf16x8 pa0, bf16x8 pa1, bf16x8 pa2, bf16x8 pa3) {
;     ...
;     const s16x4 l0 = tr_read<VOFF(0, 0)>(vb), h0 = tr_read<VOFF(0, 1)>(vb), l1 = tr_read<VOFF(1, 0)>(vb), h1 = tr_read<VOFF(1, 1)>(vb);
;     const s16x4 l2 = tr_read<VOFF(2, 0)>(vb), h2 = tr_read<VOFF(2, 1)>(vb), l3 = tr_read<VOFF(3, 0)>(vb), h3 = tr_read<VOFF(3, 1)>(vb);
;     ...
;     asm volatile("s_waitcnt lgkmcnt(0)" ::: "memory"); SBAR();
;     ...
;     od = __builtin_amdgcn_mfma_f32_32x32x16_bf16(pa0, PK(l0, h0), od, 0, 0, 0);
;     od = __builtin_amdgcn_mfma_f32_32x32x16_bf16(pa1, PK(l1, h1), od, 0, 0, 0);
;     od = __builtin_amdgcn_mfma_f32_32x32x16_bf16(pa2, PK(l2, h2), od, 0, 0, 0);
;     od = __builtin_amdgcn_mfma_f32_32x32x16_bf16(pa3, PK(l3, h3), od, 0, 0, 0);
.LBB0_1153:
	s_or_b64 exec, exec, s[0:1]
	s_add_u32 s100, s10, 0x2fc30000
	s_addc_u32 s101, s11, 0
	s_nop 0
	global_load_dwordx4 v[4:7], v156, s[100:101]
	ds_read_b64_tr_b16 v[74:75], v171 offset:0
	ds_read_b64_tr_b16 v[76:77], v171 offset:0x400
	ds_read_b64_tr_b16 v[182:183], v171 offset:0x800
	ds_read_b64_tr_b16 v[184:185], v171 offset:0xc00
	ds_read_b64_tr_b16 v[186:187], v171 offset:0x1000
	ds_read_b64_tr_b16 v[188:189], v171 offset:0x1400
	ds_read_b64_tr_b16 v[202:203], v171 offset:0x1800
	ds_read_b64_tr_b16 v[204:205], v171 offset:0x1c00
	s_waitcnt lgkmcnt(6)
	s_nop 0
	v_mfma_f32_32x32x16_bf16 v[30:45], v[8:11], v[74:77], v[30:45]
	ds_read_b64_tr_b16 v[74:75], v171 offset:0x200
	ds_read_b64_tr_b16 v[76:77], v171 offset:0x600
	s_waitcnt lgkmcnt(6)
	v_mfma_f32_32x32x16_bf16 v[30:45], v[62:65], v[182:185], v[30:45]
	ds_read_b64_tr_b16 v[182:183], v171 offset:0xa00
	ds_read_b64_tr_b16 v[184:185], v171 offset:0xe00
	s_waitcnt lgkmcnt(6)
	v_mfma_f32_32x32x16_bf16 v[30:45], v[66:69], v[186:189], v[30:45]
	ds_read_b64_tr_b16 v[186:187], v171 offset:0x1200
	ds_read_b64_tr_b16 v[188:189], v171 offset:0x1600
	s_waitcnt lgkmcnt(6)
	v_mfma_f32_32x32x16_bf16 v[30:45], v[70:73], v[202:205], v[30:45]
	ds_read_b64_tr_b16 v[202:203], v171 offset:0x1a00
	ds_read_b64_tr_b16 v[204:205], v171 offset:0x1e00
	s_waitcnt lgkmcnt(6)
	v_mfma_f32_32x32x16_bf16 v[14:29], v[8:11], v[74:77], v[14:29]
	v_max_f32_e32 v8, v94, v95
	v_max3_f32 v8, v8, v96, v97
	v_max3_f32 v8, v8, v98, v99
	v_max3_f32 v8, v8, v100, v101
	v_max3_f32 v8, v8, v102, v103
	s_waitcnt lgkmcnt(4)
	v_mfma_f32_32x32x16_bf16 v[14:29], v[62:65], v[182:185], v[14:29]
	v_max3_f32 v8, v8, v104, v105
	v_max3_f32 v8, v8, v106, v107
	v_max3_f32 v8, v8, v108, v109
	v_max3_f32 v8, v8, v78, v79
	v_max3_f32 v8, v8, v80, v81
	v_max3_f32 v8, v8, v82, v83
	v_max3_f32 v8, v8, v84, v85
	s_waitcnt lgkmcnt(2)
	v_mfma_f32_32x32x16_bf16 v[14:29], v[66:69], v[186:189], v[14:29]
	v_max3_f32 v8, v8, v86, v87
	v_max3_f32 v8, v8, v88, v89
	v_max3_f32 v8, v8, v90, v91
	v_max3_f32 v8, v8, v92, v93
	s_waitcnt lgkmcnt(0)
	v_mfma_f32_32x32x16_bf16 v[14:29], v[70:73], v[202:205], v[14:29]
	v_cmp_ge_f32_e32 vcc, s33, v8
	s_cmp_eq_u64 vcc, exec
	s_cselect_b32 s100, 0, 1
	v_mov_b32_e32 v181, 1.0
	s_cbranch_scc1 .LBB0_1155
	v_mov_b32_e32 v9, v8
	s_nop 1
	v_permlane32_swap_b32_e32 v8, v9
	v_max_f32_e32 v8, v8, v9
	v_max_f32_e32 v8, v8, v8
	v_max_f32_e32 v8, 0, v8
	v_exp_f32_e64 v181, -v8
	v_add_f32_e32 v168, v168, v8
	v_xor_b32_e32 v46, 0x80000000, v168
	v_pk_add_f32 v[94:95], v[94:95], v[8:9] op_sel_hi:[1,0] neg_lo:[0,1] neg_hi:[0,1]
	v_pk_add_f32 v[96:97], v[96:97], v[8:9] op_sel_hi:[1,0] neg_lo:[0,1] neg_hi:[0,1]
	v_pk_add_f32 v[98:99], v[98:99], v[8:9] op_sel_hi:[1,0] neg_lo:[0,1] neg_hi:[0,1]
	v_pk_add_f32 v[100:101], v[100:101], v[8:9] op_sel_hi:[1,0] neg_lo:[0,1] neg_hi:[0,1]
	v_pk_add_f32 v[102:103], v[102:103], v[8:9] op_sel_hi:[1,0] neg_lo:[0,1] neg_hi:[0,1]
	v_pk_add_f32 v[104:105], v[104:105], v[8:9] op_sel_hi:[1,0] neg_lo:[0,1] neg_hi:[0,1]
	v_pk_add_f32 v[106:107], v[106:107], v[8:9] op_sel_hi:[1,0] neg_lo:[0,1] neg_hi:[0,1]
	v_pk_add_f32 v[108:109], v[108:109], v[8:9] op_sel_hi:[1,0] neg_lo:[0,1] neg_hi:[0,1]
	v_sub_f32_e32 v93, v93, v8
	v_sub_f32_e32 v92, v92, v8
	v_sub_f32_e32 v91, v91, v8
	v_sub_f32_e32 v90, v90, v8
	v_sub_f32_e32 v89, v89, v8
	v_sub_f32_e32 v88, v88, v8
	v_sub_f32_e32 v87, v87, v8
	v_sub_f32_e32 v86, v86, v8
	v_sub_f32_e32 v85, v85, v8
	v_sub_f32_e32 v84, v84, v8
	v_sub_f32_e32 v83, v83, v8
	v_sub_f32_e32 v82, v82, v8
	v_sub_f32_e32 v81, v81, v8
	v_sub_f32_e32 v80, v80, v8
	v_sub_f32_e32 v79, v79, v8
	v_sub_f32_e32 v78, v78, v8
	v_mov_b32_e32 v47, v46
	v_mov_b32_e32 v48, v46
	v_mov_b32_e32 v49, v46
	v_mov_b32_e32 v50, v46
	v_mov_b32_e32 v51, v46
	v_mov_b32_e32 v52, v46
	v_mov_b32_e32 v53, v46
	v_mov_b32_e32 v54, v46
	v_mov_b32_e32 v55, v46
	v_mov_b32_e32 v56, v46
	v_mov_b32_e32 v57, v46
	v_mov_b32_e32 v58, v46
	v_mov_b32_e32 v59, v46
	v_mov_b32_e32 v60, v46
	v_mov_b32_e32 v61, v46

; #define SBAR() __builtin_amdgcn_sched_barrier(0)
; template <int OFF> DEVFI s16x4 tr_read(int vb) { s16x4 r; asm volatile("ds_read_b64_tr_b16 %0, %1 offset:%2" : "=&v"(r) : "v"(vb), "i"(OFF) : "memory"); return r; }
; DEVFI void partialSM2(f32x16& p0, f32x16& p1, float& mhat, f32x16& negm, float& alpha, const float thr2, const bool first) {
;     float pmax = p0[0];
; #pragma unroll
;     for (int r = 1; r < 16; ++r) pmax = fmaxf(pmax, p0[r]);
; #pragma unroll
;     for (int r = 0; r < 16; ++r) pmax = fmaxf(pmax, p1[r]);
;     { auto rr = __builtin_amdgcn_permlane32_swap(__float_as_uint(pmax), __float_as_uint(pmax), false, false);
;       pmax = fmaxf(__uint_as_float(rr[0]), __uint_as_float(rr[1])); }
;     alpha = 1.f;
;     if (first || !__all(pmax <= thr2)) {
;         const float dl = first ? pmax : fmaxf(pmax, 0.f);
;         mhat += dl; alpha = first ? 1.f : __builtin_amdgcn_exp2f(-dl);
; #pragma unroll
;         for (int r = 0; r < 16; ++r) { p0[r] -= dl; p1[r] -= dl; }
; #pragma unroll
;         for (int r = 0; r < 16; ++r) negm[r] = -mhat;
;         asm volatile("" : "+v"(negm));
; template <int NCB, int D0> DEVFI void pv_one(f32x16& od, int vb, bf16x8 pa0, bf16x8 pa1, bf16x8 pa2, bf16x8 pa3) {
;     ...
;     const s16x4 l0 = tr_read<VOFF(0, 0)>(vb), h0 = tr_read<VOFF(0, 1)>(vb), l1 = tr_read<VOFF(1, 0)>(vb), h1 = tr_read<VOFF(1, 1)>(vb);
;     const s16x4 l2 = tr_read<VOFF(2, 0)>(vb), h2 = tr_read<VOFF(2, 1)>(vb), l3 = tr_read<VOFF(3, 0)>(vb), h3 = tr_read<VOFF(3, 1)>(vb);
;     ...
;     asm volatile("s_waitcnt lgkmcnt(0)" ::: "memory"); SBAR();
;     ...
;     od = __builtin_amdgcn_mfma_f32_32x32x16_bf16(pa0, PK(l0, h0), od, 0, 0, 0);
;     od = __builtin_amdgcn_mfma_f32_32x32x16_bf16(pa1, PK(l1, h1), od, 0, 0, 0);
;     od = __builtin_amdgcn_mfma_f32_32x32x16_bf16(pa2, PK(l2, h2), od, 0, 0, 0);
;     od = __builtin_amdgcn_mfma_f32_32x32x16_bf16(pa3, PK(l3, h3), od, 0, 0, 0);
.LBB0_1165:
	ds_read_b64_tr_b16 v[160:161], v167 offset:0
	ds_read_b64_tr_b16 v[162:163], v167 offset:0x400
	ds_read_b64_tr_b16 v[182:183], v167 offset:0x800
	ds_read_b64_tr_b16 v[184:185], v167 offset:0xc00
	ds_read_b64_tr_b16 v[186:187], v167 offset:0x1000
	ds_read_b64_tr_b16 v[188:189], v167 offset:0x1400
	ds_read_b64_tr_b16 v[202:203], v167 offset:0x1800
	ds_read_b64_tr_b16 v[204:205], v167 offset:0x1c00
	s_waitcnt lgkmcnt(6)
	s_nop 0
	v_mfma_f32_32x32x16_bf16 v[30:45], v[8:11], v[160:163], v[30:45]
	ds_read_b64_tr_b16 v[160:161], v167 offset:0x200
	ds_read_b64_tr_b16 v[162:163], v167 offset:0x600
	s_waitcnt lgkmcnt(6)
	v_mfma_f32_32x32x16_bf16 v[30:45], v[78:81], v[182:185], v[30:45]
	ds_read_b64_tr_b16 v[182:183], v167 offset:0xa00
	ds_read_b64_tr_b16 v[184:185], v167 offset:0xe00
	s_waitcnt lgkmcnt(6)
	v_mfma_f32_32x32x16_bf16 v[30:45], v[82:85], v[186:189], v[30:45]
	ds_read_b64_tr_b16 v[186:187], v167 offset:0x1200
	ds_read_b64_tr_b16 v[188:189], v167 offset:0x1600
	s_waitcnt lgkmcnt(6)
	v_mfma_f32_32x32x16_bf16 v[30:45], v[86:89], v[202:205], v[30:45]
	ds_read_b64_tr_b16 v[202:203], v167 offset:0x1a00
	ds_read_b64_tr_b16 v[204:205], v167 offset:0x1e00
	s_waitcnt lgkmcnt(6)
	v_mfma_f32_32x32x16_bf16 v[14:29], v[8:11], v[160:163], v[14:29]
	v_max_f32_e32 v8, v94, v95
	v_max3_f32 v8, v8, v96, v97
	v_max3_f32 v8, v8, v98, v99
	v_max3_f32 v8, v8, v100, v101
	v_max3_f32 v8, v8, v102, v103
	s_waitcnt lgkmcnt(4)
	v_mfma_f32_32x32x16_bf16 v[14:29], v[78:81], v[182:185], v[14:29]
	v_max3_f32 v8, v8, v104, v105
	v_max3_f32 v8, v8, v106, v107
	v_max3_f32 v8, v8, v108, v109
	v_max3_f32 v8, v8, v62, v63
	v_max3_f32 v8, v8, v64, v65
	v_max3_f32 v8, v8, v66, v67
	v_max3_f32 v8, v8, v68, v69
	s_waitcnt lgkmcnt(2)
	v_mfma_f32_32x32x16_bf16 v[14:29], v[82:85], v[186:189], v[14:29]
	v_max3_f32 v8, v8, v70, v71
	v_max3_f32 v8, v8, v72, v73
	v_max3_f32 v8, v8, v74, v75
	v_max3_f32 v8, v8, v76, v77
	v_mov_b32_e32 v9, v8
	s_waitcnt lgkmcnt(0)
	v_mfma_f32_32x32x16_bf16 v[14:29], v[86:89], v[202:205], v[14:29]
	v_cmp_ge_f32_e32 vcc, s33, v9
	s_cmp_eq_u64 vcc, exec
	s_cselect_b32 s100, 0, 1
	v_mov_b32_e32 v8, 1.0
	s_cbranch_scc1 .LBB0_1167
	v_mov_b32_e32 v10, v9
	s_nop 1
	v_permlane32_swap_b32_e32 v9, v10
	v_max_f32_e32 v9, v9, v10
	v_max_f32_e32 v8, v9, v9
	v_max_f32_e32 v10, 0, v8
	v_exp_f32_e64 v8, -v10
	v_add_f32_e32 v168, v168, v10
	v_xor_b32_e32 v46, 0x80000000, v168
	v_pk_add_f32 v[94:95], v[94:95], v[10:11] op_sel_hi:[1,0] neg_lo:[0,1] neg_hi:[0,1]
	v_pk_add_f32 v[96:97], v[96:97], v[10:11] op_sel_hi:[1,0] neg_lo:[0,1] neg_hi:[0,1]
	v_pk_add_f32 v[98:99], v[98:99], v[10:11] op_sel_hi:[1,0] neg_lo:[0,1] neg_hi:[0,1]
	v_pk_add_f32 v[100:101], v[100:101], v[10:11] op_sel_hi:[1,0] neg_lo:[0,1] neg_hi:[0,1]
	v_pk_add_f32 v[102:103], v[102:103], v[10:11] op_sel_hi:[1,0] neg_lo:[0,1] neg_hi:[0,1]
	v_pk_add_f32 v[104:105], v[104:105], v[10:11] op_sel_hi:[1,0] neg_lo:[0,1] neg_hi:[0,1]
	v_pk_add_f32 v[106:107], v[106:107], v[10:11] op_sel_hi:[1,0] neg_lo:[0,1] neg_hi:[0,1]
	v_pk_add_f32 v[108:109], v[108:109], v[10:11] op_sel_hi:[1,0] neg_lo:[0,1] neg_hi:[0,1]
	v_sub_f32_e32 v77, v77, v10
	v_sub_f32_e32 v76, v76, v10
	v_sub_f32_e32 v75, v75, v10
	v_sub_f32_e32 v74, v74, v10
	v_sub_f32_e32 v73, v73, v10
	v_sub_f32_e32 v72, v72, v10
	v_sub_f32_e32 v71, v71, v10
	v_sub_f32_e32 v70, v70, v10
	v_sub_f32_e32 v69, v69, v10
	v_sub_f32_e32 v68, v68, v10
	v_sub_f32_e32 v67, v67, v10
	v_sub_f32_e32 v66, v66, v10
	v_sub_f32_e32 v65, v65, v10
	v_sub_f32_e32 v64, v64, v10
	v_sub_f32_e32 v63, v63, v10
	v_sub_f32_e32 v62, v62, v10
	v_mov_b32_e32 v47, v46
	v_mov_b32_e32 v48, v46
	v_mov_b32_e32 v49, v46
	v_mov_b32_e32 v50, v46
	v_mov_b32_e32 v51, v46
	v_mov_b32_e32 v52, v46
	v_mov_b32_e32 v53, v46
	v_mov_b32_e32 v54, v46
	v_mov_b32_e32 v55, v46
	v_mov_b32_e32 v56, v46
	v_mov_b32_e32 v57, v46
	v_mov_b32_e32 v58, v46
	v_mov_b32_e32 v59, v46
	v_mov_b32_e32 v60, v46
	v_mov_b32_e32 v61, v46
